# mode-1 scan: b/kp lane%4 patterns four quads per ds_read_b128 (transposed layout), r quads / patterns / next step kk quads prefetched a phase ahead
# speedup vs baseline: 1.0075x; 1.0023x over previous
; #define LAS __attribute__((address_space(3)))
; template <int MODE> __device__ __forceinline__ void rwkv_item(const Params& P, int e, int c, int h, LAS float* slab, int lane) {
;     unsigned char* ws = P.ws;
;     const bf16* PA = (const bf16*)(ws + OFF_PA);
;     const float* DEC = (const float*)(ws + OFF_DEC); const bf16* A16 = (const bf16*)(ws + OFF_A16); const bf16* G16 = (const bf16*)(ws + OFF_G16);
;     const bf16* V16 = (const bf16*)(ws + (e == 0 ? OFF_VF : OFF_V16));
;     float* MCM = (float*)(ws + OFF_MCM); float* MCC = (float*)(ws + OFF_MCC); bf16* MIX = (bf16*)(ws + OFF_MIXE);
;     const int ch = h * 64 + lane;
;     const float mu_r = P.in[I_AMU][(size_t)e * DINA + ch], mu_k = P.in[I_AMU][(size_t)e * DINA + 512 + ch];
;     const float kkw = P.in[I_AKK][e * 512 + ch], ka = P.in[I_AKA][e * 512 + ch], rk = P.in[I_ARK][e * 512 + ch];
;     const float lnw = P.in[I_ALNW][e * 512 + ch], lnb = P.in[I_ALNB][e * 512 + ch];
;     constexpr int SB = MODE == 0 ? 4 : 8;
;     f32x2 S2[32], C2[MODE == 0 ? 32 : 1];
;     const size_t rowoff = (((size_t)c * 8 + h) * 64 + lane) * 64;
; template <int MODE> __device__ __forceinline__ void stage_rwkv_scan(const Params& P, int e, LAS unsigned char* lds) {
;     int tid = threadIdx.x; asm volatile("" : "+v"(tid)); const int lane = tid & 63, wave = __builtin_amdgcn_readfirstlane(tid >> 6);
;     LAS float* slab = (LAS float*)(lds + wave * 16384);
;     const int gw = blockIdx.x * NWAVES + wave, ngw = gridDim.x * NWAVES;
;     for (int it = gw; it < RNCH * 8; it += ngw) rwkv_item<MODE>(P, e, it >> 3, it & 7, slab, lane);
.LBB0_202:
	s_andn2_b64 vcc, exec, s[0:1]
	s_cbranch_vccnz .LBB0_213
	v_mov_b32_e32 v0, v211
	s_nop 0
	v_readfirstlane_b32 s0, v0
	s_ashr_i32 s0, s0, 6
	s_add_i32 s2, s0, s55
	s_cmpk_gt_i32 s2, 0x7ff
	s_cbranch_scc1 .LBB0_213
	s_lshl_b32 s0, s0, 14
	s_add_i32 s3, s0, 0
	s_load_dwordx2 s[0:1], s[30:31], 0x38
	s_load_dwordx8 s[12:19], s[30:31], 0x68
	s_load_dwordx2 s[8:9], s[30:31], 0x88
	s_waitcnt lgkmcnt(0)
	s_add_u32 s4, s72, 0xd880000
	s_addc_u32 s5, s73, 0
	s_add_u32 s6, s72, 0x12880000
	s_addc_u32 s7, s73, 0
	v_readlane_b32 s10, v255, 5
	s_add_u32 s26, s0, s10
	v_readlane_b32 s0, v255, 4
	s_addc_u32 s27, s1, s0
	s_add_u32 s46, s72, 0xb880000
	s_addc_u32 s47, s73, 0
	s_add_u32 s50, s72, 0xf880000
	s_addc_u32 s51, s73, 0
	v_readlane_b32 s0, v255, 3
	s_add_u32 s66, s72, s0
	s_addc_u32 s67, s73, 0
	s_add_u32 s70, s72, 0x10880000
	s_addc_u32 s71, s73, 0
	v_readlane_b32 s52, v254, 55
	v_readlane_b32 s53, v254, 56
	v_and_b32_e32 v64, 63, v0
	v_lshl_add_u32 v109, v64, 2, s3
	v_and_b32_e32 v213, 3, v64
	v_lshrrev_b32_e32 v212, 2, v64
	v_lshl_add_u32 v212, v213, 4, v212
	v_lshl_add_u32 v212, v212, 2, s3
	v_lshl_add_u32 v213, v213, 6, s3
	s_mov_b64 s[72:73], s[8:9]
	v_lshrrev_b32_e32 v114, 3, v64
	v_and_b32_e32 v115, 7, v64
	v_lshlrev_b32_e32 v175, 11, v114
	v_lshl_add_u32 v175, v115, 5, v175
	v_add_u32_e32 v175, s3, v175
	s_lshr_b32 s8, s3, 8
	s_add_i32 s8, s8, 0x20100
	v_lshl_add_u32 v208, v114, 2, s8
	v_mov_b32_e32 v209, s8

; #define LAS __attribute__((address_space(3)))
; template <int CTRL> __device__ __forceinline__ float dpp_mov(float v) { return __int_as_float(__builtin_amdgcn_update_dpp(0, __float_as_int(v), CTRL, 0xF, 0xF, true)); }
; __device__ __forceinline__ float frsq(float x) { return __builtin_amdgcn_rsqf(x); }
; __device__ __forceinline__ float wave_sum(float v) {
;     v += dpp_mov<0xB1>(v); v += dpp_mov<0x4E>(v); v += dpp_mov<0x141>(v); v += dpp_mov<0x140>(v);
;     const float s0 = __int_as_float(__builtin_amdgcn_readlane(__float_as_int(v), 0)), s1 = __int_as_float(__builtin_amdgcn_readlane(__float_as_int(v), 16));
;     const float s2 = __int_as_float(__builtin_amdgcn_readlane(__float_as_int(v), 32)), s3 = __int_as_float(__builtin_amdgcn_readlane(__float_as_int(v), 48));
;     return (s0 + s1) + (s2 + s3);
; }
; template <int MODE> __device__ __forceinline__ void rwkv_item(const Params& P, int e, int c, int h, LAS float* slab, int lane) {
;     ...
;         for (int s = 0; s < SB; ++s) {
;             const float r = r1[s + 1] + (r1[s] - r1[s + 1]) * mu_r, k = k1[s + 1] + (k1[s] - k1[s + 1]) * mu_k, a = aa[s];
;             float kk = k * kkw;
;             const float ss = wave_sum(kk * kk);
;             kk *= frsq(fmaxf(ss, 1e-24f));
;             const float b = kk * a, kp = k * (1.f + (a - 1.f) * ka);
;             LAS float* st = slab + s * 512;
;             st[lane] = dd[s]; st[64 + lane] = kk; st[128 + lane] = b; st[192 + lane] = kp; st[256 + lane] = r; st[320 + lane] = vv[s];
;             if (MODE == 1) { st[384 + lane] = wave_sum(r * kp * rk); st[448 + lane] = gg[s]; }
.Lm1_prep:
	v_lshlrev_b32_e32 v73, 16, v73
	v_lshlrev_b32_e32 v65, 16, v65
	v_lshlrev_b32_e32 v74, 16, v74
	v_lshlrev_b32_e32 v66, 16, v66
	v_lshlrev_b32_e32 v75, 16, v75
	v_lshlrev_b32_e32 v67, 16, v67
	v_lshlrev_b32_e32 v76, 16, v76
	v_lshlrev_b32_e32 v68, 16, v68
	v_lshlrev_b32_e32 v77, 16, v77
	v_lshlrev_b32_e32 v69, 16, v69
	v_lshlrev_b32_e32 v78, 16, v78
	v_lshlrev_b32_e32 v70, 16, v70
	v_lshlrev_b32_e32 v79, 16, v79
	v_lshlrev_b32_e32 v71, 16, v71
	v_lshlrev_b32_e32 v80, 16, v80
	v_lshlrev_b32_e32 v72, 16, v72
	v_sub_f32_e32 v136, v106, v73
	v_sub_f32_e32 v176, v105, v65
	v_fma_f32 v136, v116, v136, v73
	v_fma_f32 v176, v111, v176, v65
	v_lshlrev_b32_e32 v97, 16, v97
	v_mul_f32_e32 v144, v117, v136
	v_add_f32_e32 v127, -1.0, v97
	v_mul_f32_e32 v124, v144, v144
	v_fma_f32 v127, v118, v127, 1.0
	ds_write_b32 v109, v124
	v_mul_f32_e32 v136, v136, v127
	v_mul_f32_e32 v125, v176, v136
	v_mul_f32_e32 v125, v119, v125
	ds_write_b32 v109, v125 offset:1536
	v_sub_f32_e32 v137, v73, v74
	v_sub_f32_e32 v177, v65, v66
	v_fma_f32 v137, v116, v137, v74
	v_fma_f32 v177, v111, v177, v66
	v_lshlrev_b32_e32 v98, 16, v98
	v_mul_f32_e32 v145, v117, v137
	v_add_f32_e32 v127, -1.0, v98
	v_mul_f32_e32 v124, v145, v145
	v_fma_f32 v127, v118, v127, 1.0
	ds_write_b32 v109, v124 offset:2048
	v_mul_f32_e32 v137, v137, v127
	v_mul_f32_e32 v125, v177, v137
	v_mul_f32_e32 v125, v119, v125
	ds_write_b32 v109, v125 offset:3584
	v_sub_f32_e32 v138, v74, v75
	v_sub_f32_e32 v178, v66, v67
	v_fma_f32 v138, v116, v138, v75
	v_fma_f32 v178, v111, v178, v67
	v_lshlrev_b32_e32 v99, 16, v99
	v_mul_f32_e32 v146, v117, v138
	v_add_f32_e32 v127, -1.0, v99
	v_mul_f32_e32 v124, v146, v146
	v_fma_f32 v127, v118, v127, 1.0
	ds_write_b32 v109, v124 offset:4096
	v_mul_f32_e32 v138, v138, v127
	v_mul_f32_e32 v125, v178, v138
	v_mul_f32_e32 v125, v119, v125
	ds_write_b32 v109, v125 offset:5632
	v_sub_f32_e32 v139, v75, v76
	v_sub_f32_e32 v179, v67, v68
	v_fma_f32 v139, v116, v139, v76
	v_fma_f32 v179, v111, v179, v68
	v_lshlrev_b32_e32 v100, 16, v100
	v_mul_f32_e32 v147, v117, v139
	v_add_f32_e32 v127, -1.0, v100
	v_mul_f32_e32 v124, v147, v147
	v_fma_f32 v127, v118, v127, 1.0
	ds_write_b32 v109, v124 offset:6144
	v_mul_f32_e32 v139, v139, v127
	v_mul_f32_e32 v125, v179, v139
	v_mul_f32_e32 v125, v119, v125
	ds_write_b32 v109, v125 offset:7680
	v_sub_f32_e32 v140, v76, v77
	v_sub_f32_e32 v180, v68, v69
	v_fma_f32 v140, v116, v140, v77
	v_fma_f32 v180, v111, v180, v69
	v_lshlrev_b32_e32 v101, 16, v101
	v_mul_f32_e32 v148, v117, v140
	v_add_f32_e32 v127, -1.0, v101
	v_mul_f32_e32 v124, v148, v148
	v_fma_f32 v127, v118, v127, 1.0
	ds_write_b32 v109, v124 offset:8192
	v_mul_f32_e32 v140, v140, v127
	v_mul_f32_e32 v125, v180, v140
	v_mul_f32_e32 v125, v119, v125
	ds_write_b32 v109, v125 offset:9728
	v_sub_f32_e32 v141, v77, v78
	v_sub_f32_e32 v181, v69, v70
	v_fma_f32 v141, v116, v141, v78
	v_fma_f32 v181, v111, v181, v70
	v_lshlrev_b32_e32 v102, 16, v102
	v_mul_f32_e32 v149, v117, v141
	v_add_f32_e32 v127, -1.0, v102
	v_mul_f32_e32 v124, v149, v149
	v_fma_f32 v127, v118, v127, 1.0
	ds_write_b32 v109, v124 offset:10240
	v_mul_f32_e32 v141, v141, v127
	v_mul_f32_e32 v125, v181, v141
	v_mul_f32_e32 v125, v119, v125
	ds_write_b32 v109, v125 offset:11776
	v_sub_f32_e32 v142, v78, v79
	v_sub_f32_e32 v182, v70, v71
	v_fma_f32 v142, v116, v142, v79
	v_fma_f32 v182, v111, v182, v71
	v_lshlrev_b32_e32 v103, 16, v103
	v_mul_f32_e32 v150, v117, v142
	v_add_f32_e32 v127, -1.0, v103
	v_mul_f32_e32 v124, v150, v150
	v_fma_f32 v127, v118, v127, 1.0
	ds_write_b32 v109, v124 offset:12288
	v_mul_f32_e32 v142, v142, v127
	v_mul_f32_e32 v125, v182, v142
	v_mul_f32_e32 v125, v119, v125
	ds_write_b32 v109, v125 offset:13824
	v_sub_f32_e32 v143, v79, v80
	v_sub_f32_e32 v183, v71, v72
	v_fma_f32 v143, v116, v143, v80
	v_fma_f32 v183, v111, v183, v72
	v_lshlrev_b32_e32 v104, 16, v104
	v_mul_f32_e32 v151, v117, v143
	v_add_f32_e32 v127, -1.0, v104
	v_mul_f32_e32 v124, v151, v151
	v_fma_f32 v127, v118, v127, 1.0
	ds_write_b32 v109, v124 offset:14336
	v_mul_f32_e32 v143, v143, v127
	v_mul_f32_e32 v125, v183, v143
	v_mul_f32_e32 v125, v119, v125
	ds_write_b32 v109, v125 offset:15872
	v_mov_b32_e32 v106, v80
	v_mov_b32_e32 v105, v72
	s_waitcnt lgkmcnt(0)
	ds_read_b128 v[192:195], v175
	ds_read_b128 v[196:199], v175 offset:16
	ds_read_b128 v[128:131], v175 offset:1536
	ds_read_b128 v[132:135], v175 offset:1552
	s_waitcnt lgkmcnt(2)
	v_add_f32_e32 v192, v192, v193
	v_add_f32_e32 v194, v194, v195
	v_add_f32_e32 v196, v196, v197
	v_add_f32_e32 v198, v198, v199
	v_add_f32_e32 v192, v192, v194
	v_add_f32_e32 v196, v196, v198
	v_add_f32_e32 v192, v192, v196
	s_waitcnt lgkmcnt(0)
	v_add_f32_e32 v128, v128, v129
	v_add_f32_e32 v130, v130, v131
	v_add_f32_e32 v132, v132, v133
	v_add_f32_e32 v134, v134, v135
	v_add_f32_e32 v128, v128, v130
	v_add_f32_e32 v132, v132, v134
	v_add_f32_e32 v128, v128, v132
	s_nop 0
	v_add_f32_dpp v192, v192, v192 quad_perm:[1,0,3,2] row_mask:0xf bank_mask:0xf bound_ctrl:1
	v_add_f32_dpp v128, v128, v128 quad_perm:[1,0,3,2] row_mask:0xf bank_mask:0xf bound_ctrl:1
	s_nop 0
	v_add_f32_dpp v192, v192, v192 quad_perm:[2,3,0,1] row_mask:0xf bank_mask:0xf bound_ctrl:1
	v_add_f32_dpp v128, v128, v128 quad_perm:[2,3,0,1] row_mask:0xf bank_mask:0xf bound_ctrl:1
	s_nop 0
	v_add_f32_dpp v192, v192, v192 row_half_mirror row_mask:0xf bank_mask:0xf bound_ctrl:1
	v_add_f32_dpp v128, v128, v128 row_half_mirror row_mask:0xf bank_mask:0xf bound_ctrl:1
	ds_write_b32 v208, v192
	ds_write_b32 v208, v128 offset:32
	s_waitcnt lgkmcnt(0)
; #define LAS __attribute__((address_space(3)))
; __device__ __forceinline__ float frsq(float x) { return __builtin_amdgcn_rsqf(x); }
; template <int MODE> __device__ __forceinline__ void rwkv_item(const Params& P, int e, int c, int h, LAS float* slab, int lane) {
;     ...
;             const float r = r1[s + 1] + (r1[s] - r1[s + 1]) * mu_r, k = k1[s + 1] + (k1[s] - k1[s + 1]) * mu_k, a = aa[s];
;             float kk = k * kkw;
;             const float ss = wave_sum(kk * kk);
;             kk *= frsq(fmaxf(ss, 1e-24f));
;             const float b = kk * a, kp = k * (1.f + (a - 1.f) * ka);
;             LAS float* st = slab + s * 512;
;             st[lane] = dd[s]; st[64 + lane] = kk; st[128 + lane] = b; st[192 + lane] = kp; st[256 + lane] = r; st[320 + lane] = vv[s];
;             if (MODE == 1) { st[384 + lane] = wave_sum(r * kp * rk); st[448 + lane] = gg[s]; }
	ds_read_b128 v[184:187], v209
	ds_read_b128 v[188:191], v209 offset:16
	ds_read_b128 v[200:203], v209 offset:32
	ds_read_b128 v[204:207], v209 offset:48
	s_waitcnt lgkmcnt(0)
	v_max_f32_e32 v127, 0x179abe15, v184
	v_rsq_f32_e32 v127, v127
	v_lshlrev_b32_e32 v81, 16, v81
	v_mul_f32_e32 v144, v144, v127
	v_mul_f32_e32 v124, v97, v144
	v_mul_f32_e32 v144, v144, v107
	v_mul_f32_e32 v107, v107, v89
	v_rcp_f32_e32 v127, v107
	v_mul_f32_e32 v176, v176, v107
	v_lshlrev_b32_e32 v167, 16, v167
	v_mul_f32_e32 v124, v124, v127
	v_mul_f32_e32 v136, v136, v127
	ds_write2st64_b32 v109, v144, v176 offset0:1 offset1:4
	ds_write2st64_b32 v212, v124, v136 offset0:2 offset1:3
	ds_write2st64_b32 v109, v81, v200 offset0:5 offset1:6
	ds_write_b32 v109, v167 offset:1792
	v_max_f32_e32 v127, 0x179abe15, v185
	v_rsq_f32_e32 v127, v127
	v_lshlrev_b32_e32 v82, 16, v82
	v_mul_f32_e32 v145, v145, v127
	v_mul_f32_e32 v124, v98, v145
	v_mul_f32_e32 v145, v145, v107
	v_mul_f32_e32 v107, v107, v90
	v_rcp_f32_e32 v127, v107
	v_mul_f32_e32 v177, v177, v107
	v_lshlrev_b32_e32 v168, 16, v168
	v_mul_f32_e32 v124, v124, v127
	v_mul_f32_e32 v137, v137, v127
	ds_write2st64_b32 v109, v145, v177 offset0:9 offset1:12
	ds_write2st64_b32 v212, v124, v137 offset0:10 offset1:11
	ds_write2st64_b32 v109, v82, v201 offset0:13 offset1:14
	ds_write_b32 v109, v168 offset:3840
	v_max_f32_e32 v127, 0x179abe15, v186
	v_rsq_f32_e32 v127, v127
	v_lshlrev_b32_e32 v83, 16, v83
	v_mul_f32_e32 v146, v146, v127
	v_mul_f32_e32 v124, v99, v146
	v_mul_f32_e32 v146, v146, v107
	v_mul_f32_e32 v107, v107, v91
	v_rcp_f32_e32 v127, v107
	v_mul_f32_e32 v178, v178, v107
	v_lshlrev_b32_e32 v169, 16, v169
	v_mul_f32_e32 v124, v124, v127
	v_mul_f32_e32 v138, v138, v127
	ds_write2st64_b32 v109, v146, v178 offset0:17 offset1:20
	ds_write2st64_b32 v212, v124, v138 offset0:18 offset1:19
	ds_write2st64_b32 v109, v83, v202 offset0:21 offset1:22
	ds_write_b32 v109, v169 offset:5888
	v_max_f32_e32 v127, 0x179abe15, v187
	v_rsq_f32_e32 v127, v127
	v_lshlrev_b32_e32 v84, 16, v84
	v_mul_f32_e32 v147, v147, v127
	v_mul_f32_e32 v124, v100, v147
	v_mul_f32_e32 v147, v147, v107
	v_mul_f32_e32 v107, v107, v92
	v_rcp_f32_e32 v127, v107
	v_mul_f32_e32 v179, v179, v107
	v_lshlrev_b32_e32 v170, 16, v170
	v_mul_f32_e32 v124, v124, v127
	v_mul_f32_e32 v139, v139, v127
	ds_write2st64_b32 v109, v147, v179 offset0:25 offset1:28
	ds_write2st64_b32 v212, v124, v139 offset0:26 offset1:27
	ds_write2st64_b32 v109, v84, v203 offset0:29 offset1:30
	ds_write_b32 v109, v170 offset:7936
	v_max_f32_e32 v127, 0x179abe15, v188
	v_rsq_f32_e32 v127, v127
	v_lshlrev_b32_e32 v85, 16, v85
	v_mul_f32_e32 v148, v148, v127
	v_mul_f32_e32 v124, v101, v148
	v_mul_f32_e32 v148, v148, v107
	v_mul_f32_e32 v107, v107, v93
	v_rcp_f32_e32 v127, v107
	v_mul_f32_e32 v180, v180, v107
	v_lshlrev_b32_e32 v171, 16, v171
	v_mul_f32_e32 v124, v124, v127
	v_mul_f32_e32 v140, v140, v127
	ds_write2st64_b32 v109, v148, v180 offset0:33 offset1:36
	ds_write2st64_b32 v212, v124, v140 offset0:34 offset1:35
	ds_write2st64_b32 v109, v85, v204 offset0:37 offset1:38
	ds_write_b32 v109, v171 offset:9984
	v_max_f32_e32 v127, 0x179abe15, v189
	v_rsq_f32_e32 v127, v127
	v_lshlrev_b32_e32 v86, 16, v86
	v_mul_f32_e32 v149, v149, v127
	v_mul_f32_e32 v124, v102, v149
	v_mul_f32_e32 v149, v149, v107
	v_mul_f32_e32 v107, v107, v94
	v_rcp_f32_e32 v127, v107
	v_mul_f32_e32 v181, v181, v107
	v_lshlrev_b32_e32 v172, 16, v172
	v_mul_f32_e32 v124, v124, v127
	v_mul_f32_e32 v141, v141, v127
	ds_write2st64_b32 v109, v149, v181 offset0:41 offset1:44
	ds_write2st64_b32 v212, v124, v141 offset0:42 offset1:43
	ds_write2st64_b32 v109, v86, v205 offset0:45 offset1:46
	ds_write_b32 v109, v172 offset:12032
	v_max_f32_e32 v127, 0x179abe15, v190
	v_rsq_f32_e32 v127, v127
	v_lshlrev_b32_e32 v87, 16, v87
	v_mul_f32_e32 v150, v150, v127
	v_mul_f32_e32 v124, v103, v150
	v_mul_f32_e32 v150, v150, v107
	v_mul_f32_e32 v107, v107, v95
	v_rcp_f32_e32 v127, v107
	v_mul_f32_e32 v182, v182, v107
	v_lshlrev_b32_e32 v173, 16, v173
	v_mul_f32_e32 v124, v124, v127
	v_mul_f32_e32 v142, v142, v127
	ds_write2st64_b32 v109, v150, v182 offset0:49 offset1:52
	ds_write2st64_b32 v212, v124, v142 offset0:50 offset1:51
	ds_write2st64_b32 v109, v87, v206 offset0:53 offset1:54
	ds_write_b32 v109, v173 offset:14080
	v_max_f32_e32 v127, 0x179abe15, v191
	v_rsq_f32_e32 v127, v127
	v_lshlrev_b32_e32 v88, 16, v88
	v_mul_f32_e32 v151, v151, v127
	v_mul_f32_e32 v124, v104, v151
	v_mul_f32_e32 v151, v151, v107
	v_mul_f32_e32 v107, v107, v96
	v_rcp_f32_e32 v127, v107
	v_mul_f32_e32 v183, v183, v107
	v_lshlrev_b32_e32 v174, 16, v174
	v_mul_f32_e32 v124, v124, v127
	v_mul_f32_e32 v143, v143, v127
	ds_write2st64_b32 v109, v151, v183 offset0:57 offset1:60
	ds_write2st64_b32 v212, v124, v143 offset0:58 offset1:59
	ds_write2st64_b32 v109, v88, v207 offset0:61 offset1:62
	ds_write_b32 v109, v174 offset:16128
	s_cmp_eq_u32 s1, 7
	s_cbranch_scc1 .Lm1_noload
; #define RW_LD_DOT(buf, hb) do { _Pragma("unroll") for (int q_ = 0; q_ < DB; ++q_) kd[buf][q_] = *(const LAS f32x4*)(st + 64 + 4 * (DB * (hb) + q_)); } while (0)
; #define RW_LD_UPD(buf, qb) do { _Pragma("unroll") for (int q_ = 0; q_ < UB; ++q_) { const int qq_ = UB * (qb) + q_; \
;                 wq[buf][q_] = *(const LAS f32x4*)(st + 4 * qq_); bq[buf][q_] = *(const LAS f32x4*)(st + 128 + 4 * qq_); kq[buf][q_] = *(const LAS f32x4*)(st + 192 + 4 * qq_); \
;                 if (MODE == 1) rq[buf][q_] = *(const LAS f32x4*)(st + 256 + 4 * qq_); } } while (0)
; template <int MODE> __device__ __forceinline__ void rwkv_item(const Params& P, int e, int c, int h, LAS float* slab, int lane) {
;     ...
;             if (NB == 2) RW_LD_DOT(0, 0);
;             const float v = st[320 + lane];
; #pragma unroll
;             for (int hb = 0; hb < NDB; ++hb) {
;                 if (NB == 2) { if (hb + 1 < NDB) RW_LD_DOT((hb + 1) & 1, hb + 1); else RW_LD_UPD(0, 0); } else RW_LD_DOT(0, hb);
;                 __builtin_amdgcn_sched_barrier(0);
; #pragma unroll
;                 for (int q = 0; q < DB; ++q) {
;                     const int qq = DB * hb + q; const f32x4 k4 = kd[hb & (NB - 1)][q];
;                     aS0 += S2[2 * qq] * (f32x2){k4.x, k4.y}; aS1 += S2[2 * qq + 1] * (f32x2){k4.z, k4.w};
;                     if (MODE == 0) { aC0 += C2[2 * qq] * (f32x2){k4.x, k4.y}; aC1 += C2[2 * qq + 1] * (f32x2){k4.z, k4.w}; }
;                 }
;                 __builtin_amdgcn_sched_barrier(0);
;             }
	global_load_ushort v65, v108, s[52:53]
	global_load_ushort v73, v108, s[52:53] offset:1024
	v_add_u32_e32 v115, 0xe00, v108
	global_load_ushort v66, v115, s[52:53]
	global_load_ushort v74, v115, s[52:53] offset:1024
	v_add_u32_e32 v122, 0x1c00, v108
	global_load_ushort v67, v122, s[52:53]
	global_load_ushort v75, v122, s[52:53] offset:1024
	v_add_u32_e32 v123, 0x2a00, v108
	global_load_ushort v68, v123, s[52:53]
	global_load_ushort v76, v123, s[52:53] offset:1024
	v_add_u32_e32 v114, 0x3800, v108
	global_load_ushort v69, v114, s[52:53]
	global_load_ushort v77, v114, s[52:53] offset:1024
	v_add_u32_e32 v115, 0x4600, v108
	global_load_ushort v70, v115, s[52:53]
	global_load_ushort v78, v115, s[52:53] offset:1024
	v_add_u32_e32 v122, 0x5400, v108
	global_load_ushort v71, v122, s[52:53]
	global_load_ushort v79, v122, s[52:53] offset:1024
	v_add_u32_e32 v123, 0x6200, v108
	global_load_ushort v72, v123, s[52:53]
	global_load_ushort v80, v123, s[52:53] offset:1024
	v_add_u32_e32 v114, 0x1000, v110
	global_load_ushort v81, v110, s[66:67]
	global_load_ushort v82, v110, s[66:67] offset:1024
	global_load_ushort v83, v110, s[66:67] offset:2048
	global_load_ushort v84, v110, s[66:67] offset:3072
	global_load_ushort v85, v114, s[66:67]
	global_load_ushort v86, v114, s[66:67] offset:1024
	global_load_ushort v87, v114, s[66:67] offset:2048
	global_load_ushort v88, v114, s[66:67] offset:3072
	global_load_ushort v97, v110, s[4:5]
	global_load_ushort v98, v110, s[4:5] offset:1024
	global_load_ushort v99, v110, s[4:5] offset:2048
	global_load_ushort v100, v110, s[4:5] offset:3072
	global_load_ushort v101, v114, s[4:5]
	global_load_ushort v102, v114, s[4:5] offset:1024
	global_load_ushort v103, v114, s[4:5] offset:2048
	global_load_ushort v104, v114, s[4:5] offset:3072
	global_load_ushort v167, v110, s[50:51]
	global_load_ushort v168, v110, s[50:51] offset:1024
	global_load_ushort v169, v110, s[50:51] offset:2048
	global_load_ushort v170, v110, s[50:51] offset:3072
	global_load_ushort v171, v114, s[50:51]
	global_load_ushort v172, v114, s[50:51] offset:1024
	global_load_ushort v173, v114, s[50:51] offset:2048
	global_load_ushort v174, v114, s[50:51] offset:3072
	v_add_u32_e32 v115, 0x1000, v112
	v_add_u32_e32 v122, 0x2000, v112
	v_add_u32_e32 v123, 0x3000, v112
	global_load_dword v89, v112, s[46:47]
	global_load_dword v90, v112, s[46:47] offset:2048
	global_load_dword v91, v115, s[46:47]
	global_load_dword v92, v115, s[46:47] offset:2048
	global_load_dword v93, v122, s[46:47]
	global_load_dword v94, v122, s[46:47] offset:2048
	global_load_dword v95, v123, s[46:47]
	global_load_dword v96, v123, s[46:47] offset:2048
	v_add_u32_e32 v108, 0x7000, v108
	v_add_u32_e32 v110, 0x2000, v110
	v_add_u32_e32 v112, 0x4000, v112
.Lm1_noload:
	s_waitcnt lgkmcnt(0)
	s_mov_b32 s11, 0
	v_mov_b32_e32 v196, s3
	ds_read_b128 v[136:139], v196 offset:256
	ds_read_b128 v[140:143], v196 offset:272
	ds_read_b128 v[144:147], v196 offset:288
	ds_read_b128 v[148:151], v196 offset:304
	ds_read_b128 v[176:179], v196 offset:320
	ds_read_b128 v[180:183], v196 offset:336
	ds_read_b128 v[184:187], v196 offset:352
	ds_read_b128 v[188:191], v196 offset:368
	ds_write_b32 v109, v198
.Lm1_step:
	s_add_i32 s8, s3, s11
	v_add_u32_e32 v197, s11, v109
	v_mov_b32_e32 v196, s8
	v_add_u32_e32 v199, s11, v213
	ds_read_b32 v194, v197 offset:1280
	ds_read_b128 v[124:127], v199 offset:512
	ds_read_b128 v[230:233], v199 offset:768
	ds_read_b128 v[128:131], v199 offset:528
	ds_read_b128 v[234:237], v199 offset:784
	s_waitcnt lgkmcnt(13)
	v_pk_fma_f32 v[158:159], v[0:1], v[136:137], 0 op_sel_hi:[1,1,0]
	v_pk_fma_f32 v[160:161], v[2:3], v[138:139], 0 op_sel_hi:[1,1,0]
	ds_read_b128 v[136:139], v196 offset:384
	s_waitcnt lgkmcnt(13)
	v_pk_fma_f32 v[158:159], v[4:5], v[140:141], v[158:159]
	v_pk_fma_f32 v[160:161], v[6:7], v[142:143], v[160:161]
	ds_read_b128 v[140:143], v196 offset:400
	s_waitcnt lgkmcnt(13)
	v_pk_fma_f32 v[158:159], v[8:9], v[144:145], v[158:159]
	v_pk_fma_f32 v[160:161], v[10:11], v[146:147], v[160:161]
	ds_read_b128 v[144:147], v196 offset:416
	s_waitcnt lgkmcnt(13)
	v_pk_fma_f32 v[158:159], v[12:13], v[148:149], v[158:159]
	v_pk_fma_f32 v[160:161], v[14:15], v[150:151], v[160:161]
	ds_read_b128 v[148:151], v196 offset:432
	s_waitcnt lgkmcnt(13)
	v_pk_fma_f32 v[158:159], v[16:17], v[176:177], v[158:159]
	v_pk_fma_f32 v[160:161], v[18:19], v[178:179], v[160:161]
	ds_read_b128 v[176:179], v196 offset:448
	s_waitcnt lgkmcnt(13)
	v_pk_fma_f32 v[158:159], v[20:21], v[180:181], v[158:159]
	v_pk_fma_f32 v[160:161], v[22:23], v[182:183], v[160:161]
	ds_read_b128 v[180:183], v196 offset:464
	s_waitcnt lgkmcnt(13)
	v_pk_fma_f32 v[158:159], v[24:25], v[184:185], v[158:159]
	v_pk_fma_f32 v[160:161], v[26:27], v[186:187], v[160:161]
	ds_read_b128 v[184:187], v196 offset:480
	s_waitcnt lgkmcnt(13)
	v_pk_fma_f32 v[158:159], v[28:29], v[188:189], v[158:159]
	v_pk_fma_f32 v[160:161], v[30:31], v[190:191], v[160:161]
	ds_read_b128 v[188:191], v196 offset:496
	s_waitcnt lgkmcnt(7)
	v_pk_fma_f32 v[158:159], v[32:33], v[136:137], v[158:159]
	v_pk_fma_f32 v[160:161], v[34:35], v[138:139], v[160:161]
	ds_read_b128 v[136:139], v196 offset:1024
	s_waitcnt lgkmcnt(7)
	v_pk_fma_f32 v[158:159], v[36:37], v[140:141], v[158:159]
	v_pk_fma_f32 v[160:161], v[38:39], v[142:143], v[160:161]
	ds_read_b128 v[140:143], v196 offset:1040
	s_waitcnt lgkmcnt(7)
	v_pk_fma_f32 v[158:159], v[40:41], v[144:145], v[158:159]
	v_pk_fma_f32 v[160:161], v[42:43], v[146:147], v[160:161]
	ds_read_b128 v[144:147], v196 offset:1056
	s_waitcnt lgkmcnt(7)
; #define LAS __attribute__((address_space(3)))
; #define RW_LD_UPD(buf, qb) do { _Pragma("unroll") for (int q_ = 0; q_ < UB; ++q_) { const int qq_ = UB * (qb) + q_; \
;                 wq[buf][q_] = *(const LAS f32x4*)(st + 4 * qq_); bq[buf][q_] = *(const LAS f32x4*)(st + 128 + 4 * qq_); kq[buf][q_] = *(const LAS f32x4*)(st + 192 + 4 * qq_); \
;                 if (MODE == 1) rq[buf][q_] = *(const LAS f32x4*)(st + 256 + 4 * qq_); } } while (0)
; template <int MODE> __device__ __forceinline__ void rwkv_item(const Params& P, int e, int c, int h, LAS float* slab, int lane) {
;     ...
;             const float nsk = -((aS0.x + aS0.y) + (aS1.x + aS1.y));
;             const float nskC = -((aC0.x + aC0.y) + (aC1.x + aC1.y));
;             f32x2 y0 = {0.f, 0.f}, y1 = {0.f, 0.f};
; #pragma unroll
;             for (int qb = 0; qb < NUB; ++qb) {
;                 if (NB == 2) { if (qb + 1 < NUB) RW_LD_UPD((qb + 1) & 1, qb + 1); } else RW_LD_UPD(0, qb);
;                 __builtin_amdgcn_sched_barrier(0);
; #pragma unroll
;                 for (int q = 0; q < UB; ++q) {
;                     const int qq = UB * qb + q;
;                     const f32x4 w4 = wq[qb & (NB - 1)][q], b4 = bq[qb & (NB - 1)][q], k4 = kq[qb & (NB - 1)][q];
;                     if (MODE == 0) {
;                         S2[2 * qq] = S2[2 * qq] * (f32x2){w4.x, w4.y} + (f32x2){b4.x, b4.y} * nsk;
;                         S2[2 * qq + 1] = S2[2 * qq + 1] * (f32x2){w4.z, w4.w} + (f32x2){b4.z, b4.w} * nsk;
;                         C2[2 * qq] = C2[2 * qq] * (f32x2){w4.x, w4.y} + (f32x2){b4.x, b4.y} * nskC + (f32x2){k4.x, k4.y} * v;
;                         C2[2 * qq + 1] = C2[2 * qq + 1] * (f32x2){w4.z, w4.w} + (f32x2){b4.z, b4.w} * nskC + (f32x2){k4.z, k4.w} * v;
;                     } else {
;                         S2[2 * qq] = S2[2 * qq] * (f32x2){w4.x, w4.y} + (f32x2){b4.x, b4.y} * nsk + (f32x2){k4.x, k4.y} * v;
;                         S2[2 * qq + 1] = S2[2 * qq + 1] * (f32x2){w4.z, w4.w} + (f32x2){b4.z, b4.w} * nsk + (f32x2){k4.z, k4.w} * v;
;                         const f32x4 r4 = rq[qb & (NB - 1)][q]; y0 += S2[2 * qq] * (f32x2){r4.x, r4.y}; y1 += S2[2 * qq + 1] * (f32x2){r4.z, r4.w};
;                     }
;                 }
;                 __builtin_amdgcn_sched_barrier(0);
;             }
;     ...
;             if (MODE == 1) ((LAS float*)st)[lane] = (y0.x + y0.y) + (y1.x + y1.y);
	v_pk_fma_f32 v[158:159], v[44:45], v[148:149], v[158:159]
	v_pk_fma_f32 v[160:161], v[46:47], v[150:151], v[160:161]
	ds_read_b128 v[148:151], v196 offset:1072
	s_waitcnt lgkmcnt(7)
	v_pk_fma_f32 v[158:159], v[48:49], v[176:177], v[158:159]
	v_pk_fma_f32 v[160:161], v[50:51], v[178:179], v[160:161]
	ds_read_b128 v[176:179], v196 offset:1088
	s_waitcnt lgkmcnt(7)
	v_pk_fma_f32 v[158:159], v[52:53], v[180:181], v[158:159]
	v_pk_fma_f32 v[160:161], v[54:55], v[182:183], v[160:161]
	ds_read_b128 v[180:183], v196 offset:1104
	s_waitcnt lgkmcnt(7)
	v_pk_fma_f32 v[158:159], v[56:57], v[184:185], v[158:159]
	v_pk_fma_f32 v[160:161], v[58:59], v[186:187], v[160:161]
	ds_read_b128 v[184:187], v196 offset:1120
	s_waitcnt lgkmcnt(7)
	v_pk_fma_f32 v[158:159], v[60:61], v[188:189], v[158:159]
	v_pk_fma_f32 v[160:161], v[62:63], v[190:191], v[160:161]
	ds_read_b128 v[188:191], v196 offset:1136
	v_add_f32_e32 v192, v158, v159
	v_add_f32_e32 v198, v160, v161
	v_sub_f32_e64 v193, -v198, v192
	s_nop 1
	v_mfma_f32_4x4x1_16b_f32 v[0:3], v124, v193, v[0:3]
	v_mfma_f32_4x4x1_16b_f32 v[4:7], v125, v193, v[4:7]
	v_mfma_f32_4x4x1_16b_f32 v[0:3], v230, v194, v[0:3]
	v_mfma_f32_4x4x1_16b_f32 v[8:11], v126, v193, v[8:11]
	v_mfma_f32_4x4x1_16b_f32 v[4:7], v231, v194, v[4:7]
	v_mfma_f32_4x4x1_16b_f32 v[12:15], v127, v193, v[12:15]
	v_mfma_f32_4x4x1_16b_f32 v[8:11], v232, v194, v[8:11]
	ds_read_b128 v[124:127], v199 offset:544
	v_mfma_f32_4x4x1_16b_f32 v[16:19], v128, v193, v[16:19]
	v_mfma_f32_4x4x1_16b_f32 v[12:15], v233, v194, v[12:15]
	ds_read_b128 v[230:233], v199 offset:800
	v_mfma_f32_4x4x1_16b_f32 v[20:23], v129, v193, v[20:23]
	v_mfma_f32_4x4x1_16b_f32 v[16:19], v234, v194, v[16:19]
	v_mfma_f32_4x4x1_16b_f32 v[24:27], v130, v193, v[24:27]
	v_mfma_f32_4x4x1_16b_f32 v[20:23], v235, v194, v[20:23]
	v_mfma_f32_4x4x1_16b_f32 v[28:31], v131, v193, v[28:31]
	v_mfma_f32_4x4x1_16b_f32 v[24:27], v236, v194, v[24:27]
	ds_read_b128 v[128:131], v199 offset:560
	s_waitcnt lgkmcnt(2)
	v_mfma_f32_4x4x1_16b_f32 v[32:35], v124, v193, v[32:35]
	v_mfma_f32_4x4x1_16b_f32 v[28:31], v237, v194, v[28:31]
	ds_read_b128 v[234:237], v199 offset:816
	v_mfma_f32_4x4x1_16b_f32 v[36:39], v125, v193, v[36:39]
	s_waitcnt lgkmcnt(2)
	v_mfma_f32_4x4x1_16b_f32 v[32:35], v230, v194, v[32:35]
	v_mfma_f32_4x4x1_16b_f32 v[40:43], v126, v193, v[40:43]
	v_mfma_f32_4x4x1_16b_f32 v[36:39], v231, v194, v[36:39]
	v_mfma_f32_4x4x1_16b_f32 v[44:47], v127, v193, v[44:47]
	v_mfma_f32_4x4x1_16b_f32 v[40:43], v232, v194, v[40:43]
	s_waitcnt lgkmcnt(1)
	v_mfma_f32_4x4x1_16b_f32 v[48:51], v128, v193, v[48:51]
	v_mfma_f32_4x4x1_16b_f32 v[44:47], v233, v194, v[44:47]
	v_mfma_f32_4x4x1_16b_f32 v[52:55], v129, v193, v[52:55]
	s_waitcnt lgkmcnt(0)
	v_mfma_f32_4x4x1_16b_f32 v[48:51], v234, v194, v[48:51]
	v_mfma_f32_4x4x1_16b_f32 v[56:59], v130, v193, v[56:59]
	v_mfma_f32_4x4x1_16b_f32 v[52:55], v235, v194, v[52:55]
	v_mfma_f32_4x4x1_16b_f32 v[60:63], v131, v193, v[60:63]
	v_mfma_f32_4x4x1_16b_f32 v[56:59], v236, v194, v[56:59]
	s_nop 0
	v_mfma_f32_4x4x1_16b_f32 v[60:63], v237, v194, v[60:63]
	v_pk_fma_f32 v[162:163], v[136:137], v[0:1], 0 op_sel_hi:[1,1,0]
	v_pk_fma_f32 v[164:165], v[138:139], v[2:3], 0 op_sel_hi:[1,1,0]
	ds_read_b128 v[136:139], v196 offset:1152
	v_pk_fma_f32 v[162:163], v[140:141], v[4:5], v[162:163]
	v_pk_fma_f32 v[164:165], v[142:143], v[6:7], v[164:165]
	ds_read_b128 v[140:143], v196 offset:1168
	v_pk_fma_f32 v[162:163], v[144:145], v[8:9], v[162:163]
	v_pk_fma_f32 v[164:165], v[146:147], v[10:11], v[164:165]
	ds_read_b128 v[144:147], v196 offset:1184
	v_pk_fma_f32 v[162:163], v[148:149], v[12:13], v[162:163]
	v_pk_fma_f32 v[164:165], v[150:151], v[14:15], v[164:165]
	ds_read_b128 v[148:151], v196 offset:1200
	v_pk_fma_f32 v[162:163], v[176:177], v[16:17], v[162:163]
	v_pk_fma_f32 v[164:165], v[178:179], v[18:19], v[164:165]
	ds_read_b128 v[176:179], v196 offset:1216
	v_pk_fma_f32 v[162:163], v[180:181], v[20:21], v[162:163]
	v_pk_fma_f32 v[164:165], v[182:183], v[22:23], v[164:165]
	ds_read_b128 v[180:183], v196 offset:1232
	v_pk_fma_f32 v[162:163], v[184:185], v[24:25], v[162:163]
	v_pk_fma_f32 v[164:165], v[186:187], v[26:27], v[164:165]
	ds_read_b128 v[184:187], v196 offset:1248
	v_pk_fma_f32 v[162:163], v[188:189], v[28:29], v[162:163]
	v_pk_fma_f32 v[164:165], v[190:191], v[30:31], v[164:165]
	ds_read_b128 v[188:191], v196 offset:1264
	s_waitcnt lgkmcnt(7)
	v_pk_fma_f32 v[162:163], v[136:137], v[32:33], v[162:163]
	v_pk_fma_f32 v[164:165], v[138:139], v[34:35], v[164:165]
	ds_read_b128 v[136:139], v196 offset:2304
	s_waitcnt lgkmcnt(7)
	v_pk_fma_f32 v[162:163], v[140:141], v[36:37], v[162:163]
	v_pk_fma_f32 v[164:165], v[142:143], v[38:39], v[164:165]
	ds_read_b128 v[140:143], v196 offset:2320
	s_waitcnt lgkmcnt(7)
	v_pk_fma_f32 v[162:163], v[144:145], v[40:41], v[162:163]
	v_pk_fma_f32 v[164:165], v[146:147], v[42:43], v[164:165]
	ds_read_b128 v[144:147], v196 offset:2336
	s_waitcnt lgkmcnt(7)
	v_pk_fma_f32 v[162:163], v[148:149], v[44:45], v[162:163]
	v_pk_fma_f32 v[164:165], v[150:151], v[46:47], v[164:165]
	ds_read_b128 v[148:151], v196 offset:2352
	s_waitcnt lgkmcnt(7)
	v_pk_fma_f32 v[162:163], v[176:177], v[48:49], v[162:163]
	v_pk_fma_f32 v[164:165], v[178:179], v[50:51], v[164:165]
	ds_read_b128 v[176:179], v196 offset:2368
	s_waitcnt lgkmcnt(7)
	v_pk_fma_f32 v[162:163], v[180:181], v[52:53], v[162:163]
	v_pk_fma_f32 v[164:165], v[182:183], v[54:55], v[164:165]
	ds_read_b128 v[180:183], v196 offset:2384
	s_waitcnt lgkmcnt(7)
	v_pk_fma_f32 v[162:163], v[184:185], v[56:57], v[162:163]
	v_pk_fma_f32 v[164:165], v[186:187], v[58:59], v[164:165]
	ds_read_b128 v[184:187], v196 offset:2400
	s_waitcnt lgkmcnt(7)
	v_pk_fma_f32 v[162:163], v[188:189], v[60:61], v[162:163]
	v_pk_fma_f32 v[164:165], v[190:191], v[62:63], v[164:165]
	ds_read_b128 v[188:191], v196 offset:2416
	v_add_f32_e32 v198, v162, v163
	v_add_f32_e32 v192, v164, v165
	v_add_f32_e32 v198, v192, v198
	s_addk_i32 s11, 0x800
	ds_write_b32 v197, v198
	s_cmpk_eq_i32 s11, 0x4000
	s_cbranch_scc0 .Lm1_step
; #define LAS __attribute__((address_space(3)))
; __device__ __forceinline__ unsigned f2bf(float f) { unsigned u = __float_as_uint(f); return (u + 0x7fffu + ((u >> 16) & 1u)) >> 16; }
; __device__ __forceinline__ float frsq(float x) { return __builtin_amdgcn_rsqf(x); }
; #define LDS_WAIT() asm volatile("s_waitcnt lgkmcnt(0)" ::: "memory")
; template <int MODE> __device__ __forceinline__ void rwkv_item(const Params& P, int e, int c, int h, LAS float* slab, int lane) {
;     ...
;         if (MODE == 1) {
;             LDS_WAIT();
; #pragma unroll
;             for (int s = 0; s < SB; ++s) {
;                 const LAS float* st = slab + s * 512;
;                 const float y = st[lane], v = st[320 + lane];
;                 const float mean = wave_sum(y) * (1.f / 64.f), d = y - mean;
;                 const float var = wave_sum(d * d) * (1.f / 64.f);
;                 const float yn = d * frsq(var + 64e-5f) * lnw + lnb;
;                 MIX[(size_t)(tb + s) * D + ch] = (bf16)f2bf((yn + st[384 + lane] * v) * st[448 + lane]);
;             }
;         }
;         LDS_WAIT();
	s_waitcnt lgkmcnt(0)
	s_waitcnt vmcnt(48)
	ds_read_b128 v[192:195], v175
	ds_read_b128 v[196:199], v175 offset:16
	ds_read2st64_b32 v[136:137], v109 offset0:0 offset1:5
	ds_read2st64_b32 v[138:139], v109 offset0:8 offset1:13
	ds_read2st64_b32 v[140:141], v109 offset0:16 offset1:21
	ds_read2st64_b32 v[142:143], v109 offset0:24 offset1:29
	ds_read2st64_b32 v[144:145], v109 offset0:32 offset1:37
	ds_read2st64_b32 v[146:147], v109 offset0:40 offset1:45
	ds_read2st64_b32 v[148:149], v109 offset0:48 offset1:53
	ds_read2st64_b32 v[150:151], v109 offset0:56 offset1:61
	s_waitcnt lgkmcnt(8)
	v_add_f32_e32 v192, v192, v193
	v_add_f32_e32 v194, v194, v195
	v_add_f32_e32 v196, v196, v197
	v_add_f32_e32 v198, v198, v199
	v_add_f32_e32 v192, v192, v194
	v_add_f32_e32 v196, v196, v198
	v_add_f32_e32 v192, v192, v196
	s_nop 1
	v_add_f32_dpp v192, v192, v192 quad_perm:[1,0,3,2] row_mask:0xf bank_mask:0xf bound_ctrl:1
	s_nop 1
	v_add_f32_dpp v192, v192, v192 quad_perm:[2,3,0,1] row_mask:0xf bank_mask:0xf bound_ctrl:1
	s_nop 1
	v_add_f32_dpp v192, v192, v192 row_half_mirror row_mask:0xf bank_mask:0xf bound_ctrl:1
	ds_write_b32 v208, v192
	s_waitcnt lgkmcnt(0)
	ds_read_b128 v[184:187], v209
	ds_read_b128 v[188:191], v209 offset:16
	s_waitcnt lgkmcnt(0)
	v_fmamk_f32 v136, v184, 0xbc800000, v136
	v_mul_f32_e32 v124, v136, v136
	ds_write_b32 v109, v124
	v_fmamk_f32 v138, v185, 0xbc800000, v138
	v_mul_f32_e32 v124, v138, v138
	ds_write_b32 v109, v124 offset:2048
	v_fmamk_f32 v140, v186, 0xbc800000, v140
	v_mul_f32_e32 v124, v140, v140
	ds_write_b32 v109, v124 offset:4096
	v_fmamk_f32 v142, v187, 0xbc800000, v142
	v_mul_f32_e32 v124, v142, v142
	ds_write_b32 v109, v124 offset:6144
	v_fmamk_f32 v144, v188, 0xbc800000, v144
	v_mul_f32_e32 v124, v144, v144
	ds_write_b32 v109, v124 offset:8192
	v_fmamk_f32 v146, v189, 0xbc800000, v146
	v_mul_f32_e32 v124, v146, v146
	ds_write_b32 v109, v124 offset:10240
	v_fmamk_f32 v148, v190, 0xbc800000, v148
	v_mul_f32_e32 v124, v148, v148
	ds_write_b32 v109, v124 offset:12288
	v_fmamk_f32 v150, v191, 0xbc800000, v150
	v_mul_f32_e32 v124, v150, v150
	ds_write_b32 v109, v124 offset:14336
	s_waitcnt lgkmcnt(0)
	ds_read_b128 v[192:195], v175
	ds_read_b128 v[196:199], v175 offset:16
	s_waitcnt lgkmcnt(0)
	v_add_f32_e32 v192, v192, v193
	v_add_f32_e32 v194, v194, v195
	v_add_f32_e32 v196, v196, v197
	v_add_f32_e32 v198, v198, v199
	v_add_f32_e32 v192, v192, v194
	v_add_f32_e32 v196, v196, v198
	v_add_f32_e32 v192, v192, v196
	s_nop 1
	v_add_f32_dpp v192, v192, v192 quad_perm:[1,0,3,2] row_mask:0xf bank_mask:0xf bound_ctrl:1
	s_nop 1
	v_add_f32_dpp v192, v192, v192 quad_perm:[2,3,0,1] row_mask:0xf bank_mask:0xf bound_ctrl:1
	s_nop 1
	v_add_f32_dpp v192, v192, v192 row_half_mirror row_mask:0xf bank_mask:0xf bound_ctrl:1
	ds_write_b32 v208, v192
	s_waitcnt lgkmcnt(0)
	ds_read_b128 v[184:187], v209
	ds_read_b128 v[188:191], v209 offset:16
	ds_read2st64_b32 v[128:129], v109 offset0:6 offset1:7
	ds_read2st64_b32 v[130:131], v109 offset0:14 offset1:15
	ds_read2st64_b32 v[132:133], v109 offset0:22 offset1:23
	ds_read2st64_b32 v[134:135], v109 offset0:30 offset1:31
	ds_read2st64_b32 v[192:193], v109 offset0:38 offset1:39
	ds_read2st64_b32 v[194:195], v109 offset0:46 offset1:47
	ds_read2st64_b32 v[196:197], v109 offset0:54 offset1:55
	ds_read2st64_b32 v[198:199], v109 offset0:62 offset1:63
	s_waitcnt lgkmcnt(7)
	v_fmamk_f32 v124, v184, 0x3c800000, v221
	v_rsq_f32_e32 v124, v124
	v_add_u32_e32 v127, 0x0, v113
	v_mul_f32_e32 v136, v136, v124
	v_fma_f32 v136, v120, v136, v121
	v_fmac_f32_e32 v136, v137, v128
	v_mul_f32_e32 v136, v129, v136
	v_bfe_u32 v125, v136, 16, 1
	v_add3_u32 v126, v136, v125, s33
	global_store_short_d16_hi v127, v126, s[70:71]
	s_waitcnt lgkmcnt(6)
	v_fmamk_f32 v124, v185, 0x3c800000, v221
	v_rsq_f32_e32 v124, v124
	v_add_u32_e32 v127, 0x800, v113
	v_mul_f32_e32 v138, v138, v124
	v_fma_f32 v138, v120, v138, v121
	v_fmac_f32_e32 v138, v139, v130
	v_mul_f32_e32 v138, v131, v138
	v_bfe_u32 v125, v138, 16, 1
	v_add3_u32 v126, v138, v125, s33
	global_store_short_d16_hi v127, v126, s[70:71]
	s_waitcnt lgkmcnt(5)
	v_fmamk_f32 v124, v186, 0x3c800000, v221
	v_rsq_f32_e32 v124, v124
	v_add_u32_e32 v127, 0x1000, v113
	v_mul_f32_e32 v140, v140, v124
	v_fma_f32 v140, v120, v140, v121
	v_fmac_f32_e32 v140, v141, v132
	v_mul_f32_e32 v140, v133, v140
	v_bfe_u32 v125, v140, 16, 1
	v_add3_u32 v126, v140, v125, s33
	global_store_short_d16_hi v127, v126, s[70:71]
	s_waitcnt lgkmcnt(4)
	v_fmamk_f32 v124, v187, 0x3c800000, v221
	v_rsq_f32_e32 v124, v124
	v_add_u32_e32 v127, 0x1800, v113
	v_mul_f32_e32 v142, v142, v124
	v_fma_f32 v142, v120, v142, v121
	v_fmac_f32_e32 v142, v143, v134
	v_mul_f32_e32 v142, v135, v142
	v_bfe_u32 v125, v142, 16, 1
	v_add3_u32 v126, v142, v125, s33
	global_store_short_d16_hi v127, v126, s[70:71]
	s_waitcnt lgkmcnt(3)
	v_fmamk_f32 v124, v188, 0x3c800000, v221
	v_rsq_f32_e32 v124, v124
	v_add_u32_e32 v127, 0x2000, v113
	v_mul_f32_e32 v144, v144, v124
	v_fma_f32 v144, v120, v144, v121
	v_fmac_f32_e32 v144, v145, v192
	v_mul_f32_e32 v144, v193, v144
	v_bfe_u32 v125, v144, 16, 1
	v_add3_u32 v126, v144, v125, s33
	global_store_short_d16_hi v127, v126, s[70:71]
	s_waitcnt lgkmcnt(2)
	v_fmamk_f32 v124, v189, 0x3c800000, v221
	v_rsq_f32_e32 v124, v124
	v_add_u32_e32 v127, 0x2800, v113
	v_mul_f32_e32 v146, v146, v124
	v_fma_f32 v146, v120, v146, v121
	v_fmac_f32_e32 v146, v147, v194
	v_mul_f32_e32 v146, v195, v146
	v_bfe_u32 v125, v146, 16, 1
	v_add3_u32 v126, v146, v125, s33
	global_store_short_d16_hi v127, v126, s[70:71]
	s_waitcnt lgkmcnt(1)
	v_fmamk_f32 v124, v190, 0x3c800000, v221
	v_rsq_f32_e32 v124, v124
	v_add_u32_e32 v127, 0x3000, v113
	v_mul_f32_e32 v148, v148, v124
	v_fma_f32 v148, v120, v148, v121
	v_fmac_f32_e32 v148, v149, v196
	v_mul_f32_e32 v148, v197, v148
	v_bfe_u32 v125, v148, 16, 1
	v_add3_u32 v126, v148, v125, s33
	global_store_short_d16_hi v127, v126, s[70:71]
	s_waitcnt lgkmcnt(0)
	v_fmamk_f32 v124, v191, 0x3c800000, v221
	v_rsq_f32_e32 v124, v124
	v_add_u32_e32 v127, 0x3800, v113
	v_mul_f32_e32 v150, v150, v124
	v_fma_f32 v150, v120, v150, v121
	v_fmac_f32_e32 v150, v151, v198
	v_mul_f32_e32 v150, v199, v150
	v_bfe_u32 v125, v150, 16, 1
	v_add3_u32 v126, v150, v125, s33
	global_store_short_d16_hi v127, v126, s[70:71]
	v_add_u32_e32 v113, 0x4000, v113
	s_add_i32 s1, s1, 1
	s_cmp_eq_u32 s1, 8
	s_cbranch_scc0 .Lm1_sub
	s_add_i32 s2, s2, s58
	s_cmpk_gt_i32 s2, 0x7ff
	s_cbranch_scc0 .LBB0_205
	s_load_dwordx2 s[72:73], s[30:31], 0x118
	v_readlane_b32 s12, v253, 17
	v_readlane_b32 s13, v253, 18
	v_readlane_b32 s67, v255, 14
	v_readlane_b32 s71, v255, 15
	v_readlane_b32 s51, v255, 16
